# P4: the eight group-norm gain/bias loads are loop-invariant per thread: loaded once before the loop (22 loads per iteration instead of 30), vmcnt waits re-derived
# baseline (speedup 1.0000x reference)
; __device__ __forceinline__ float bflo(unsigned v) { return __uint_as_float(v << 16); }
; __device__ __forceinline__ float bfhi(unsigned v) { return __uint_as_float(v & 0xffff0000u); }
; __device__ void phase_rwkv_out(const Params& p, int bid, int nb) {
;   const int tid = threadIdx.x, lane = tid & 63, wave = tid >> 6;
;   const int r = lane & 15, g = lane >> 4, wq = wave & 3;
;   for (int it2 = bid; it2 < 2048; it2 += nb) {
;     const int item = it2 * 2 + (wave >> 2);
;     const int b = item >> 9, hd = (item >> 6) & 7, c = item & 63;
;     const int tl = wq * 16 + r;
;     const u16* ryp = p.Ry + (size_t)item * 4096 + tl * 64;
;     const u16* hsp = p.Hs + (size_t)item * 4096;
;     f32x4 acc[4];
; #pragma unroll
;     for (int jt = 0; jt < 4; ++jt) { const u32x2 yw = *(const u32x2*)(p.Y0 + (size_t)item * 4096 + tl * 64 + jt * 16 + 4 * g); acc[jt][0] = bflo(yw.x); acc[jt][1] = bfhi(yw.x); acc[jt][2] = bflo(yw.y); acc[jt][3] = bfhi(yw.y); }
; #pragma unroll
;     for (int ks = 0; ks < 2; ++ks) {
;       const bf16x8 bfr = *(const bf16x8*)(ryp + ks * 32 + g * 8);
; #pragma unroll
;       for (int jt = 0; jt < 4; ++jt) {
;         const bf16x8 afr = *(const bf16x8*)(hsp + (jt * 16 + r) * 64 + ks * 32 + g * 8);
;     ...
;         acc[jt] = __builtin_amdgcn_mfma_f32_16x16x32_bf16(afr, bfr, acc[jt], 0, 0, 0);
;     ...
;       }
;     }
.LBB0_496:
	s_or_b64 exec, exec, s[4:5]
	s_cmpk_gt_i32 s2, 0x7ff
	s_waitcnt lgkmcnt(0)
	s_barrier
	s_cbranch_scc1 .LBB0_499
	v_xor_b32_e32 v3, 16, v1
	s_load_dwordx2 s[8:9], s[0:1], 0x130
	s_load_dwordx2 s[10:11], s[0:1], 0xf8
	s_load_dwordx4 s[4:7], s[0:1], 0xe8
	v_cmp_lt_i32_e32 vcc, v3, v157
	v_lshrrev_b32_e32 v2, 2, v223
	v_and_or_b32 v2, v2, 48, v174
	v_cndmask_b32_e32 v3, v1, v3, vcc
	v_cmp_lt_i32_e32 vcc, v156, v157
	v_mov_b32_e32 v5, 0
	v_lshlrev_b32_e32 v10, 4, v115
	v_cndmask_b32_e32 v4, v1, v156, vcc
	v_lshlrev_b32_e32 v24, 2, v4
	v_lshlrev_b32_e32 v4, 7, v2
	s_waitcnt lgkmcnt(0)
	v_lshl_add_u64 v[8:9], s[4:5], 0, v[4:5]
	v_mov_b32_e32 v11, v5
	v_lshl_add_u64 v[6:7], s[8:9], 0, v[4:5]
	v_lshl_add_u64 v[8:9], v[8:9], 0, v[10:11]
	v_lshl_add_u64 v[10:11], s[10:11], 0, v[10:11]
	v_lshl_add_u64 v[14:15], s[6:7], 0, v[4:5]
	s_load_dwordx4 s[4:7], s[0:1], 0x58
	s_load_dwordx4 s[8:11], s[0:1], 0xc0
	v_lshrrev_b32_e32 v17, 8, v223
	v_lshlrev_b32_e32 v16, 6, v174
	v_or_b32_e32 v18, 0x800, v16
	v_or_b32_e32 v20, 0xc00, v16
	v_lshlrev_b32_e32 v12, 3, v115
	v_mov_b32_e32 v13, v5
	v_lshlrev_b32_e32 v4, 6, v17
	v_lshlrev_b32_e32 v3, 2, v3
	v_lshl_add_u64 v[6:7], v[6:7], 0, v[12:13]
	v_lshl_add_u64 v[12:13], v[14:15], 0, v[12:13]
	v_lshl_add_u32 v25, s2, 7, v4
	s_lshl_b32 s12, s50, 7
	v_lshl_add_u32 v14, s2, 1, v17
	s_lshl_b32 s13, s50, 1
	v_lshlrev_b32_e32 v16, 1, v16
	v_mov_b32_e32 v17, v5
	v_lshlrev_b32_e32 v18, 1, v18
	v_mov_b32_e32 v19, v5
	v_lshlrev_b32_e32 v20, 1, v20
	v_mov_b32_e32 v21, v5
	s_movk_i32 s14, 0xfc0
	s_movk_i32 s15, 0x1c0
	v_mov_b32_e32 v26, 0x3a27c5ac
	s_mov_b32 s16, s2
	v_and_or_b32 v210, v14, s15, v114
	v_lshlrev_b32_e32 v210, 2, v210
	s_waitcnt lgkmcnt(0)
	global_load_dwordx4 v[178:181], v210, s[4:5]
	global_load_dwordx4 v[182:185], v210, s[6:7]
	global_load_dwordx4 v[186:189], v210, s[4:5] offset:64
	global_load_dwordx4 v[190:193], v210, s[6:7] offset:64
	global_load_dwordx4 v[194:197], v210, s[4:5] offset:128
	global_load_dwordx4 v[198:201], v210, s[6:7] offset:128
	global_load_dwordx4 v[202:205], v210, s[4:5] offset:192
	global_load_dwordx4 v[206:209], v210, s[6:7] offset:192
.LBB0_498:
	v_ashrrev_i32_e32 v15, 31, v14
	v_ashrrev_i32_e32 v22, 9, v14
	v_and_or_b32 v4, v14, s15, v114
	v_lshlrev_b64 v[36:37], 13, v[14:15]
	v_ashrrev_i32_e32 v23, 31, v22
	v_lshlrev_b32_e32 v15, 2, v4
	v_lshl_add_u64 v[38:39], v[6:7], 0, v[36:37]
	v_lshl_add_u64 v[44:45], v[8:9], 0, v[36:37]
	v_lshl_add_u64 v[46:47], v[10:11], 0, v[36:37]
	v_lshlrev_b64 v[76:77], 12, v[22:23]
	s_waitcnt lgkmcnt(0)
	v_lshl_add_u64 v[22:23], v[12:13], 0, v[36:37]
	global_load_dwordx2 v[78:79], v[38:39], off
	global_load_dwordx2 v[82:83], v[38:39], off offset:32
	global_load_dwordx2 v[84:85], v[38:39], off offset:64
	global_load_dwordx2 v[86:87], v[38:39], off offset:96
	s_nop 0
	global_load_dwordx4 v[36:39], v[44:45], off
	global_load_dwordx4 v[40:43], v[44:45], off offset:64
	v_lshl_add_u64 v[68:69], v[46:47], 0, v[16:17]
	v_lshl_add_u64 v[70:71], v[46:47], 0, v[18:19]
	v_lshl_add_u64 v[72:73], v[46:47], 0, v[20:21]
	v_lshl_add_u64 v[74:75], v[46:47], 0, 64
	global_load_dwordx2 v[88:89], v[22:23], off
	global_load_dwordx4 v[44:47], v[68:69], off
	global_load_dwordx4 v[48:51], v[68:69], off offset:2048
	global_load_dwordx4 v[52:55], v[70:71], off
	global_load_dwordx4 v[56:59], v[72:73], off
	global_load_dwordx4 v[60:63], v[68:69], off offset:64
	global_load_dwordx4 v[64:67], v[68:69], off offset:2112
	v_lshl_add_u64 v[80:81], v[74:75], 0, v[18:19]
	v_lshl_add_u64 v[90:91], v[74:75], 0, v[20:21]
	global_load_dwordx4 v[68:71], v[80:81], off
	global_load_dwordx4 v[72:75], v[90:91], off
	v_and_or_b32 v27, v25, s14, v76
	v_or_b32_e32 v76, v27, v2
	v_lshlrev_b64 v[80:81], 10, v[76:77]
	v_lshlrev_b64 v[90:91], 11, v[76:77]
	v_lshl_add_u64 v[92:93], s[8:9], 0, v[80:81]
	v_lshlrev_b32_e32 v4, 1, v4
	v_lshl_add_u64 v[176:177], v[92:93], 0, v[4:5]
	global_load_dwordx2 v[120:121], v[22:23], off offset:32
	global_load_dwordx2 v[122:123], v[176:177], off offset:32
	global_load_dwordx2 v[132:133], v[22:23], off offset:64
	global_load_dwordx2 v[134:135], v[176:177], off offset:64
	global_load_dwordx2 v[144:145], v[22:23], off offset:96
	global_load_dwordx2 v[146:147], v[176:177], off offset:96
	s_add_i32 s16, s16, s50
	v_add_u32_e32 v14, s13, v14
	s_cmpk_lt_i32 s16, 0x800
	v_add_u32_e32 v25, s12, v25
	s_waitcnt vmcnt(20)
	v_lshlrev_b32_e32 v76, 16, v78
	v_and_b32_e32 v77, 0xffff0000, v78
	v_lshlrev_b32_e32 v78, 16, v79
	v_and_b32_e32 v79, 0xffff0000, v79
	s_waitcnt vmcnt(19)
	v_lshlrev_b32_e32 v80, 16, v82
	v_and_b32_e32 v81, 0xffff0000, v82
	s_waitcnt vmcnt(13)
	v_mfma_f32_16x16x32_bf16 v[44:47], v[44:47], v[36:39], v[76:79]
	v_lshlrev_b32_e32 v82, 16, v83
	v_and_b32_e32 v83, 0xffff0000, v83
	s_nop 0
	v_lshlrev_b32_e32 v76, 16, v84
	v_and_b32_e32 v77, 0xffff0000, v84
	s_waitcnt vmcnt(12)
	v_mfma_f32_16x16x32_bf16 v[48:51], v[48:51], v[36:39], v[80:83]
	v_lshlrev_b32_e32 v78, 16, v85
	v_and_b32_e32 v79, 0xffff0000, v85
	s_nop 0
	v_lshlrev_b32_e32 v80, 16, v86
	v_and_b32_e32 v81, 0xffff0000, v86
	v_lshlrev_b32_e32 v82, 16, v87
	v_and_b32_e32 v83, 0xffff0000, v87
	s_waitcnt vmcnt(11)
	v_mfma_f32_16x16x32_bf16 v[52:55], v[52:55], v[36:39], v[76:79]
	s_waitcnt vmcnt(10)
	v_mfma_f32_16x16x32_bf16 v[36:39], v[56:59], v[36:39], v[80:83]
	v_lshl_add_u64 v[58:59], v[92:93], 0, v[4:5]
	v_lshl_add_u64 v[56:57], s[10:11], 0, v[90:91]
	v_lshl_add_u64 v[56:57], v[56:57], 0, v[4:5]
	s_waitcnt vmcnt(9)
	v_mfma_f32_16x16x32_bf16 v[44:47], v[60:63], v[40:43], v[44:47]
	global_load_dwordx2 v[60:61], v[58:59], off
	v_lshlrev_b32_e32 v62, 16, v89
	v_and_b32_e32 v63, 0xffff0000, v89
	s_waitcnt vmcnt(9)
; __device__ __forceinline__ unsigned pk2(float lo, float hi) { f32x2_t v = {lo, hi}; bf16x2_t b = __builtin_convertvector(v, bf16x2_t); return __builtin_bit_cast(unsigned, b); }
; __device__ __forceinline__ float bflo(unsigned v) { return __uint_as_float(v << 16); }
; __device__ __forceinline__ float bfhi(unsigned v) { return __uint_as_float(v & 0xffff0000u); }
; __device__ void phase_rwkv_out(const Params& p, int bid, int nb) {
;     ...
;     float s = 0.f;
; #pragma unroll
;     for (int jt = 0; jt < 4; ++jt)
; #pragma unroll
;       for (int e = 0; e < 4; ++e) s += acc[jt][e];
;     s += __shfl_xor(s, 16); s += __shfl_xor(s, 32);
;     const float mu = s * (1.f / 64.f);
;     float vs = 0.f;
; #pragma unroll
;     for (int jt = 0; jt < 4; ++jt)
; #pragma unroll
;       for (int e = 0; e < 4; ++e) { const float d = acc[jt][e] - mu; vs += d * d; }
;     vs += __shfl_xor(vs, 16); vs += __shfl_xor(vs, 32);
;     const float rstd = __builtin_amdgcn_rsqf(vs * (1.f / 64.f) + 64e-5f);
;     const size_t tok = (size_t)b * SEQ + c * 64 + tl;
; #pragma unroll
;     for (int jt = 0; jt < 4; ++jt) {
;       const int v = jt * 16 + 4 * g, cc = hd * 64 + v;
;       const f32x4 gg = *(const f32x4*)(p.gn_gain + cc), gb = *(const f32x4*)(p.gn_bias + cc);
;       const u32x2 bvw = *(const u32x2*)(p.BV + (size_t)item * 4096 + tl * 64 + v);
;       const u32x2 gw = *(const u32x2*)(p.GB + tok * 512 + cc);
;       float o[4];
;       const float bvf[4] = {bflo(bvw.x), bfhi(bvw.x), bflo(bvw.y), bfhi(bvw.y)};
;       const float gf[4] = {bflo(gw.x), bfhi(gw.x), bflo(gw.y), bfhi(gw.y)};
; #pragma unroll
;       for (int e = 0; e < 4; ++e) {
;     ...
;         o[e] = bvf[e] * gf[e];
;     ...
;         o[e] = ((acc[jt][e] - mu) * rstd * gg[e] + gb[e]) * gf[e];
;     ...
;         o[e] = ((acc[jt][e] - mu) * rstd * gg[e] + gb[e] + bvf[e]) * gf[e];
;     ...
;       }
;       u32x2 w; w.x = pk2(o[0], o[1]); w.y = pk2(o[2], o[3]);
;       *(u32x2*)(p.Ymix + tok * 1024 + 512 + cc) = w;
;     }
	v_mfma_f32_16x16x32_bf16 v[48:51], v[64:67], v[40:43], v[48:51]
	v_lshlrev_b32_e32 v64, 16, v88
	s_nop 1
	v_add_f32_e32 v4, 0, v44
	v_add_f32_e32 v4, v45, v4
	v_add_f32_e32 v4, v46, v4
	v_add_f32_e32 v4, v47, v4
	s_waitcnt vmcnt(8)
	v_mfma_f32_16x16x32_bf16 v[52:55], v[68:71], v[40:43], v[52:55]
	v_add_f32_e32 v4, v48, v4
	v_add_f32_e32 v4, v49, v4
	v_add_f32_e32 v4, v50, v4
	v_add_f32_e32 v4, v51, v4
	s_waitcnt vmcnt(7)
	v_mfma_f32_16x16x32_bf16 v[36:39], v[72:75], v[40:43], v[36:39]
	s_nop 1
	v_add_f32_e32 v4, v52, v4
	v_add_f32_e32 v4, v53, v4
	v_add_f32_e32 v4, v54, v4
	v_add_f32_e32 v4, v55, v4
	v_and_b32_e32 v65, 0xffff0000, v88
	s_nop 0
	v_add_f32_e32 v4, v36, v4
	v_add_f32_e32 v4, v37, v4
	v_add_f32_e32 v4, v38, v4
	v_add_f32_e32 v4, v39, v4
	ds_bpermute_b32 v27, v3, v4
	s_waitcnt lgkmcnt(0)
	v_add_f32_e32 v4, v4, v27
	ds_bpermute_b32 v27, v24, v4
	s_waitcnt lgkmcnt(0)
	v_add_f32_e32 v4, v4, v27
	v_mul_f32_e32 v4, 0x3c800000, v4
	v_pk_add_f32 v[44:45], v[44:45], v[4:5] op_sel_hi:[1,0] neg_lo:[0,1] neg_hi:[0,1]
	v_pk_add_f32 v[42:43], v[46:47], v[4:5] op_sel_hi:[1,0] neg_lo:[0,1] neg_hi:[0,1]
	v_pk_mul_f32 v[72:73], v[44:45], v[44:45]
	v_pk_add_f32 v[40:41], v[54:55], v[4:5] op_sel_hi:[1,0] neg_lo:[0,1] neg_hi:[0,1]
	v_pk_add_f32 v[36:37], v[36:37], v[4:5] op_sel_hi:[1,0] neg_lo:[0,1] neg_hi:[0,1]
	v_pk_add_f32 v[38:39], v[38:39], v[4:5] op_sel_hi:[1,0] neg_lo:[0,1] neg_hi:[0,1]
	v_pk_add_f32 v[46:47], v[50:51], v[4:5] op_sel_hi:[1,0] neg_lo:[0,1] neg_hi:[0,1]
	v_pk_add_f32 v[48:49], v[48:49], v[4:5] op_sel_hi:[1,0] neg_lo:[0,1] neg_hi:[0,1]
	v_pk_add_f32 v[50:51], v[52:53], v[4:5] op_sel_hi:[1,0] neg_lo:[0,1] neg_hi:[0,1]
	v_pk_mul_f32 v[70:71], v[42:43], v[42:43]
	v_add_f32_e32 v4, v72, v73
	v_add_f32_e32 v4, v70, v4
	v_pk_mul_f32 v[76:77], v[48:49], v[48:49]
	v_add_f32_e32 v4, v71, v4
	v_add_f32_e32 v4, v76, v4
	v_pk_mul_f32 v[74:75], v[46:47], v[46:47]
	v_add_f32_e32 v4, v77, v4
	v_add_f32_e32 v4, v74, v4
	v_pk_mul_f32 v[78:79], v[50:51], v[50:51]
	v_add_f32_e32 v4, v75, v4
	v_add_f32_e32 v4, v78, v4
	v_pk_mul_f32 v[52:53], v[40:41], v[40:41]
	v_add_f32_e32 v4, v79, v4
	v_add_f32_e32 v4, v52, v4
	v_pk_mul_f32 v[54:55], v[36:37], v[36:37]
	v_add_f32_e32 v4, v53, v4
	v_add_f32_e32 v4, v54, v4
	v_add_f32_e32 v4, v55, v4
	s_waitcnt vmcnt(0)
	v_lshlrev_b32_e32 v66, 16, v61
	v_and_b32_e32 v67, 0xffff0000, v61
	v_lshlrev_b32_e32 v68, 16, v60
	v_and_b32_e32 v69, 0xffff0000, v60
	v_pk_mul_f32 v[60:61], v[38:39], v[38:39]
	s_nop 0
	v_add_f32_e32 v4, v60, v4
	v_add_f32_e32 v4, v61, v4
	ds_bpermute_b32 v27, v3, v4
	s_waitcnt lgkmcnt(0)
	v_add_f32_e32 v4, v4, v27
	ds_bpermute_b32 v27, v24, v4
	s_waitcnt lgkmcnt(0)
	v_add_f32_e32 v4, v4, v27
	v_fmamk_f32 v4, v4, 0x3c800000, v26
	v_rsq_f32_e32 v4, v4
	s_nop 0
	v_pk_mul_f32 v[44:45], v[44:45], v[4:5] op_sel_hi:[1,0]
	v_pk_mul_f32 v[42:43], v[42:43], v[4:5] op_sel_hi:[1,0]
	v_pk_fma_f32 v[28:29], v[178:179], v[44:45], v[182:183]
	v_pk_fma_f32 v[30:31], v[180:181], v[42:43], v[184:185]
	v_pk_add_f32 v[28:29], v[28:29], v[64:65]
	v_pk_add_f32 v[30:31], v[30:31], v[62:63]
	v_pk_mul_f32 v[28:29], v[28:29], v[68:69]
	v_pk_mul_f32 v[30:31], v[30:31], v[66:67]
	v_cvt_pk_bf16_f32 v28, v28, v29
	v_cvt_pk_bf16_f32 v29, v30, v31
	global_store_dwordx2 v[56:57], v[28:29], off offset:1024
	v_pk_mul_f32 v[48:49], v[48:49], v[4:5] op_sel_hi:[1,0]
	v_pk_mul_f32 v[46:47], v[46:47], v[4:5] op_sel_hi:[1,0]
	v_pk_mul_f32 v[40:41], v[40:41], v[4:5] op_sel_hi:[1,0]
	v_lshlrev_b32_e32 v52, 16, v120
	v_and_b32_e32 v53, 0xffff0000, v120
	v_lshlrev_b32_e32 v120, 16, v121
	v_and_b32_e32 v121, 0xffff0000, v121
	v_pk_fma_f32 v[124:125], v[186:187], v[48:49], v[190:191]
	v_pk_fma_f32 v[126:127], v[188:189], v[46:47], v[192:193]
	v_lshlrev_b32_e32 v54, 16, v122
	v_and_b32_e32 v55, 0xffff0000, v122
	v_lshlrev_b32_e32 v122, 16, v123
	v_and_b32_e32 v123, 0xffff0000, v123
	v_pk_add_f32 v[124:125], v[124:125], v[52:53]
	v_pk_add_f32 v[126:127], v[126:127], v[120:121]
	v_pk_mul_f32 v[124:125], v[124:125], v[54:55]
	v_pk_mul_f32 v[126:127], v[126:127], v[122:123]
	v_cvt_pk_bf16_f32 v124, v124, v125
	v_cvt_pk_bf16_f32 v125, v126, v127
	global_store_dwordx2 v[56:57], v[124:125], off offset:1056
	v_pk_mul_f32 v[46:47], v[50:51], v[4:5] op_sel_hi:[1,0]
	v_lshlrev_b32_e32 v48, 16, v132
	v_and_b32_e32 v49, 0xffff0000, v132
	v_pk_fma_f32 v[136:137], v[194:195], v[46:47], v[198:199]
	v_lshlrev_b32_e32 v140, 16, v133
	v_and_b32_e32 v141, 0xffff0000, v133
	v_pk_fma_f32 v[138:139], v[196:197], v[40:41], v[200:201]
	v_lshlrev_b32_e32 v50, 16, v134
	v_and_b32_e32 v51, 0xffff0000, v134
	v_lshlrev_b32_e32 v132, 16, v135
	v_and_b32_e32 v133, 0xffff0000, v135
	v_pk_add_f32 v[136:137], v[136:137], v[48:49]
	v_pk_add_f32 v[138:139], v[138:139], v[140:141]
	v_pk_mul_f32 v[136:137], v[136:137], v[50:51]
	v_pk_mul_f32 v[138:139], v[138:139], v[132:133]
	v_cvt_pk_bf16_f32 v136, v136, v137
	v_cvt_pk_bf16_f32 v137, v138, v139
	global_store_dwordx2 v[56:57], v[136:137], off offset:1088
	v_pk_mul_f32 v[22:23], v[36:37], v[4:5] op_sel_hi:[1,0]
	v_pk_mul_f32 v[36:37], v[38:39], v[4:5] op_sel_hi:[1,0]
	v_lshlrev_b32_e32 v38, 16, v144
	v_and_b32_e32 v39, 0xffff0000, v144
	v_pk_fma_f32 v[22:23], v[202:203], v[22:23], v[206:207]
	v_lshlrev_b32_e32 v148, 16, v145
	v_and_b32_e32 v149, 0xffff0000, v145
	v_pk_fma_f32 v[150:151], v[204:205], v[36:37], v[208:209]
	v_lshlrev_b32_e32 v44, 16, v146
	v_and_b32_e32 v45, 0xffff0000, v146
	v_lshlrev_b32_e32 v152, 16, v147
	v_and_b32_e32 v153, 0xffff0000, v147
	v_pk_add_f32 v[22:23], v[22:23], v[38:39]
	v_pk_add_f32 v[148:149], v[150:151], v[148:149]
	v_pk_mul_f32 v[22:23], v[22:23], v[44:45]
	v_pk_mul_f32 v[148:149], v[148:149], v[152:153]
	v_cvt_pk_bf16_f32 v22, v22, v23
	v_cvt_pk_bf16_f32 v23, v148, v149
	global_store_dwordx2 v[56:57], v[22:23], off offset:1120
	s_cbranch_scc1 .LBB0_498
